# grid-barrier poll loops: s_sleep removed (tighter spin)
# speedup vs baseline: 1.0006x; 1.0006x over previous
; __device__ __forceinline__ unsigned xb_ld(unsigned* p)              { return __hip_atomic_load(p, __ATOMIC_RELAXED, __HIP_MEMORY_SCOPE_AGENT); }
; __device__ __forceinline__ void xcd_barrier_complete(unsigned* bar, unsigned x, unsigned& nloc, unsigned& nx) {
;     const unsigned G = gridDim.x * gridDim.y * gridDim.z;
;     unsigned sum, cnt, mine, sp = 0u;
;     for (;;) {
;         sum = 0u; cnt = 0u; mine = 0u;
; #pragma unroll
;         for (unsigned j = 0; j < 16; ++j) { const unsigned c = xb_ld(&bar[XB_XCNT(j)]); sum += c; cnt += (c > 0u) ? 1u : 0u; mine = (j == x) ? c : mine; }
;         if (sum == G) break;
;         __builtin_amdgcn_s_sleep(1);
;         if ((++sp & 255u) == 0u) { if (xb_ld(&bar[XB_TMO])) break; if (sp > XB_SPIN_CAP) { atomicAdd(&bar[XB_TMO], 1u); break; } }
;     }
;     nloc = mine > 0u ? mine : 1u; nx = cnt > 0u ? cnt : 1u;
; }
.LBB0_1139:
	global_load_dword v16, v1, s[84:85] offset:1024 sc1
	global_load_dword v0, v1, s[84:85] offset:1280 sc1
	s_waitcnt lgkmcnt(0)
	global_load_dword v2, v1, s[84:85] offset:1536 sc1
	global_load_dword v3, v1, s[84:85] offset:1792 sc1
	global_load_dword v4, v1, s[84:85] offset:2048 sc1
	global_load_dword v5, v1, s[84:85] offset:2304 sc1
	global_load_dword v6, v1, s[84:85] offset:2560 sc1
	global_load_dword v7, v1, s[84:85] offset:2816 sc1
	global_load_dword v8, v1, s[84:85] offset:3072 sc1
	global_load_dword v9, v1, s[84:85] offset:3328 sc1
	global_load_dword v10, v1, s[84:85] offset:3584 sc1
	global_load_dword v11, v1, s[84:85] offset:3840 sc1
	global_load_dword v12, v1, s[4:5] sc1
	global_load_dword v13, v1, s[6:7] sc1
	global_load_dword v14, v1, s[8:9] sc1
	global_load_dword v15, v1, s[10:11] sc1
	s_mov_b64 s[12:13], -1
	s_mov_b64 s[14:15], -1
	s_waitcnt vmcnt(14)
	v_add_u32_e32 v17, v0, v16
	s_waitcnt vmcnt(13)
	v_add_u32_e32 v17, v17, v2
	s_waitcnt vmcnt(12)
	v_add_u32_e32 v17, v17, v3
	s_waitcnt vmcnt(11)
	v_add_u32_e32 v17, v17, v4
	s_waitcnt vmcnt(10)
	v_add_u32_e32 v17, v17, v5
	s_waitcnt vmcnt(9)
	v_add_u32_e32 v17, v17, v6
	s_waitcnt vmcnt(8)
	v_add_u32_e32 v17, v17, v7
	s_waitcnt vmcnt(7)
	v_add_u32_e32 v17, v17, v8
	s_waitcnt vmcnt(6)
	v_add_u32_e32 v17, v17, v9
	s_waitcnt vmcnt(5)
	v_add_u32_e32 v17, v17, v10
	s_waitcnt vmcnt(4)
	v_add_u32_e32 v17, v17, v11
	s_waitcnt vmcnt(3)
	v_add_u32_e32 v17, v17, v12
	s_waitcnt vmcnt(2)
	v_add_u32_e32 v17, v17, v13
	s_waitcnt vmcnt(1)
	v_add_u32_e32 v17, v17, v14
	s_waitcnt vmcnt(0)
	v_add_u32_e32 v17, v17, v15
	v_cmp_eq_u32_e32 vcc, s18, v17
	s_cbranch_vccnz .LBB0_1138
	s_and_b32 s12, s2, 0xff
	s_cmp_eq_u32 s12, 0
	s_mov_b64 s[12:13], -1
	s_mov_b64 s[16:17], -1
	s_cbranch_scc0 .LBB0_1143
	global_load_dword v17, v1, s[84:85] offset:512 sc1
	s_waitcnt vmcnt(0)
	v_cmp_eq_u32_e32 vcc, 0, v17
	s_cbranch_vccnz .LBB0_1145
	s_mov_b64 s[16:17], 0

; __device__ __forceinline__ unsigned xb_ld(unsigned* p)              { return __hip_atomic_load(p, __ATOMIC_RELAXED, __HIP_MEMORY_SCOPE_AGENT); }
; __device__ __forceinline__ unsigned xb_add(unsigned* p, unsigned v) { return __hip_atomic_fetch_add(p, v, __ATOMIC_RELAXED, __HIP_MEMORY_SCOPE_AGENT); }
; #define XB_SPIN(cond, bar) do { unsigned _sp = 0; while (cond) { __builtin_amdgcn_s_sleep(1); \
;     if ((++_sp & 255u) == 0u) { if (xb_ld(&(bar)[XB_TMO])) break; if (_sp > XB_SPIN_CAP) { atomicAdd(&(bar)[XB_TMO], 1u); break; } } } } while (0)
; __device__ __forceinline__ void xcd_barrier(const XcdBarrier& b) {
;     ...
;             const unsigned og = xb_add(&bar[XB_TOP], 1u);
;             const unsigned tg = og / nx;
;             if (og + 1u == (tg + 1u) * nx) xb_add(&bar[XB_TOPGEN], 1u);
;             else XB_SPIN(xb_ld(&bar[XB_TOPGEN]) == tg, bar);
;             __builtin_amdgcn_fence(__ATOMIC_ACQUIRE, "agent");
;             xb_add(&bar[XB_XGEN(b.x)], 1u);
;             asm volatile("s_waitcnt vmcnt(0)" ::: "memory");
;         } else {
;             XB_SPIN(xb_ld(&bar[XB_XGEN(b.x)]) == gen, bar);
;             __builtin_amdgcn_fence(__ATOMIC_ACQUIRE, "agent");
;             asm volatile("s_waitcnt vmcnt(0)" ::: "memory");
.LBB0_1154:
	s_and_b32 s18, s2, 0xff
	s_mov_b64 s[16:17], -1
	s_cmp_lg_u32 s18, 0
	s_mov_b64 s[20:21], -1
	s_cbranch_scc1 .LBB0_1157
	global_load_dword v2, v1, s[84:85] offset:512 sc1
	s_waitcnt vmcnt(0)
	v_cmp_eq_u32_e32 vcc, 0, v2
	s_cbranch_vccnz .LBB0_1159
	s_mov_b64 s[20:21], 0
	s_mov_b64 s[18:19], -1

; __device__ __forceinline__ unsigned xb_ld(unsigned* p)              { return __hip_atomic_load(p, __ATOMIC_RELAXED, __HIP_MEMORY_SCOPE_AGENT); }
; __device__ __forceinline__ unsigned xb_add(unsigned* p, unsigned v) { return __hip_atomic_fetch_add(p, v, __ATOMIC_RELAXED, __HIP_MEMORY_SCOPE_AGENT); }
; #define XB_SPIN(cond, bar) do { unsigned _sp = 0; while (cond) { __builtin_amdgcn_s_sleep(1); \
;     if ((++_sp & 255u) == 0u) { if (xb_ld(&(bar)[XB_TMO])) break; if (_sp > XB_SPIN_CAP) { atomicAdd(&(bar)[XB_TMO], 1u); break; } } } } while (0)
; __device__ __forceinline__ void xcd_barrier(const XcdBarrier& b) {
;     ...
;             const unsigned og = xb_add(&bar[XB_TOP], 1u);
;             const unsigned tg = og / nx;
;             if (og + 1u == (tg + 1u) * nx) xb_add(&bar[XB_TOPGEN], 1u);
;             else XB_SPIN(xb_ld(&bar[XB_TOPGEN]) == tg, bar);
;             __builtin_amdgcn_fence(__ATOMIC_ACQUIRE, "agent");
;             xb_add(&bar[XB_XGEN(b.x)], 1u);
;             asm volatile("s_waitcnt vmcnt(0)" ::: "memory");
;         } else {
;             XB_SPIN(xb_ld(&bar[XB_XGEN(b.x)]) == gen, bar);
;             __builtin_amdgcn_fence(__ATOMIC_ACQUIRE, "agent");
;             asm volatile("s_waitcnt vmcnt(0)" ::: "memory");
.LBB0_1168:
	s_and_b32 s20, s2, 0xff
	s_mov_b64 s[18:19], -1
	s_cmp_lg_u32 s20, 0
	s_mov_b64 s[22:23], -1
	s_cbranch_scc1 .LBB0_1171
	global_load_dword v2, v1, s[10:11] sc1
	s_waitcnt vmcnt(0)
	v_cmp_eq_u32_e32 vcc, 0, v2
	s_cbranch_vccnz .LBB0_1173
	s_mov_b64 s[22:23], 0
	s_mov_b64 s[20:21], -1

; #define LAS __attribute__((address_space(3)))
;     __device__ __forceinline__ unsigned char* ws() const { return (unsigned char*)(__attribute__((address_space(1))) unsigned char*)ld(35); }
; __global__ void __launch_bounds__(512, 2) mega_fwd(KArgs ka) {
;     ...
;         if (step2 == 0) { grid.sync(); xbar = xcd_barrier_post((unsigned*)(p.ws() + WS_BAR), (volatile LAS unsigned*)(lds + TBL_OFF + 512)); } else xcd_barrier(xbar);
.LBB0_1189:
	global_load_dword v2, v1, s[4:5] offset:32 sc1
	s_waitcnt vmcnt(0)
	v_and_b32_e32 v2, 0xffff0000, v2
	v_cmp_ne_u32_e32 vcc, v2, v0
	s_or_b64 s[6:7], vcc, s[6:7]
	s_andn2_b64 exec, exec, s[6:7]
	s_cbranch_execnz .LBB0_1189
